# v39 + mLSTM wave-0 gate prefix scan via DPP row_shr/row_bcast (f32 adds) instead of 6 ds_bpermute rounds; last lane via v_readlane
# speedup vs baseline: 1.0217x; 1.0066x over previous
; __device__ __forceinline__ void mlstm_item(const P& p, const Ctx& c, int seg, int w, bool save) {
;     ...
;         if (c.wv == 0) {
;             float bc = plf;
; #pragma unroll
;             for (int o = 1; o < 64; o <<= 1) { const float t = __shfl_up(bc, o); if (c.lane >= o) bc += t; }
;             const float bl = __shfl(bc, 63);
;             bcum[c.lane] = bc; ipr[c.lane] = pip; wgt[c.lane] = __expf(bl - bc + pip); gin[c.lane] = __expf(bc);
;             if (c.lane == 0) gtotp[0] = __expf(bl);
.LBB0_365:
	v_mov_b32_e32 v181, v170
	v_mov_b32_e32 v180, v174
	v_mov_b32_e32 v191, v176
	s_waitcnt lgkmcnt(0)
	s_barrier
	v_cndmask_b32_e64 v4, 0, 1, s[54:55]
	v_cmp_ne_u32_e64 s[16:17], 1, v4
	s_andn2_b64 vcc, exec, s[54:55]
	s_cbranch_vccnz .LBB0_369
	s_waitcnt vmcnt(7)
	v_mov_b32_e32 v82, v3
	s_nop 1
	v_add_f32_dpp v82, v82, v82 row_shr:1 row_mask:0xf bank_mask:0xf bound_ctrl:1
	s_nop 1
	v_add_f32_dpp v82, v82, v82 row_shr:2 row_mask:0xf bank_mask:0xf bound_ctrl:1
	s_nop 1
	v_add_f32_dpp v82, v82, v82 row_shr:4 row_mask:0xf bank_mask:0xf bound_ctrl:1
	s_nop 1
	v_add_f32_dpp v82, v82, v82 row_shr:8 row_mask:0xf bank_mask:0xf bound_ctrl:1
	s_nop 1
	v_add_f32_dpp v82, v82, v82 row_bcast:15 row_mask:0xa bank_mask:0xf
	s_nop 1
	v_add_f32_dpp v82, v82, v82 row_bcast:31 row_mask:0xc bank_mask:0xf
	s_nop 1
	v_readlane_b32 s86, v82, 63
	s_nop 1
	v_mov_b32_e32 v4, s86
	ds_write_b32 v179, v82
	s_waitcnt vmcnt(6)
	ds_write_b32 v187, v177
	s_waitcnt lgkmcnt(2)
	v_sub_f32_e32 v83, v4, v82
	v_add_f32_e32 v83, v177, v83
	v_mul_f32_e32 v83, 0x3fb8aa3b, v83
	v_mul_f32_e32 v82, 0x3fb8aa3b, v82
	v_exp_f32_e32 v83, v83
	v_exp_f32_e32 v82, v82
	ds_write_b32 v188, v83
	ds_write_b32 v189, v82
	s_and_saveexec_b64 s[86:87], s[4:5]
	s_cbranch_execz .LBB0_368
	v_mul_f32_e32 v4, 0x3fb8aa3b, v4
	v_exp_f32_e32 v4, v4
	v_mov_b32_e32 v82, s62
	ds_write_b32 v82, v4
